# v23 + hand-scheduled 8-wide scalar SwiGLU epilogue for the gate/up GEMM (same f32 ops and order, no packed ops, no dependent back-to-back VALU)
# speedup vs baseline: 1.0184x; 1.0139x over previous
.LBB0_151:
	s_and_b32 s15, s47, 1
	v_lshl_add_u32 v150, s15, 10, v146
	ds_read_b32 v152, v150
	ds_read_b32 v153, v150 offset:64
	ds_read_b32 v154, v150 offset:128
	ds_read_b32 v155, v150 offset:192
	ds_read_b32 v156, v150 offset:512
	ds_read_b32 v157, v150 offset:576
	ds_read_b32 v158, v150 offset:640
	ds_read_b32 v159, v150 offset:704
	v_lshl_or_b32 v140, s23, 7, v144
	v_lshl_add_u32 v149, s22, 8, v142
	v_ashrrev_i32_e32 v141, 31, v140
	s_andn2_b64 vcc, exec, s[2:3]
	v_mov_b64_e32 v[162:163], s[8:9]
	v_lshlrev_b64 v[164:165], 1, v[140:141]
	v_mad_i64_i32 v[160:161], s[22:23], v149, s89, v[162:163]
	s_mov_b32 s100, 0x16000
	s_mov_b32 s101, 0
	s_mov_b32 s98, 0x6e000
	s_mov_b32 s99, 0
	v_lshl_add_u64 v[160:161], v[160:161], 0, v[164:165]
	s_waitcnt lgkmcnt(0)

	v_mul_f32_e32 v122, v122, v152
	v_mul_f32_e32 v126, v126, v152
	v_mul_f32_e32 v123, v123, v152
	v_mul_f32_e32 v127, v127, v152
	v_mul_f32_e32 v124, v124, v152
	v_mul_f32_e32 v128, v128, v152
	v_mul_f32_e32 v125, v125, v152
	v_mul_f32_e32 v129, v129, v152
	v_mul_f32_e32 v114, v114, v152
	v_mul_f32_e32 v118, v118, v152
	v_mul_f32_e32 v115, v115, v152
	v_mul_f32_e32 v119, v119, v152
	v_mul_f32_e32 v116, v116, v152
	v_mul_f32_e32 v120, v120, v152
	v_mul_f32_e32 v117, v117, v152
	v_mul_f32_e32 v121, v121, v152
	v_mul_f32_e32 v166, 0xbfb8aa3b, v126
	v_mul_f32_e32 v167, 0xbfb8aa3b, v127
	v_mul_f32_e32 v168, 0xbfb8aa3b, v128
	v_mul_f32_e32 v169, 0xbfb8aa3b, v129
	v_mul_f32_e32 v170, 0xbfb8aa3b, v118
	v_mul_f32_e32 v171, 0xbfb8aa3b, v119
	v_mul_f32_e32 v172, 0xbfb8aa3b, v120
	v_mul_f32_e32 v173, 0xbfb8aa3b, v121
	v_exp_f32_e32 v166, v166
	v_exp_f32_e32 v167, v167
	v_exp_f32_e32 v168, v168
	v_exp_f32_e32 v169, v169
	v_exp_f32_e32 v170, v170
	v_exp_f32_e32 v171, v171
	v_exp_f32_e32 v172, v172
	v_exp_f32_e32 v173, v173
	v_add_f32_e32 v166, 1.0, v166
	v_add_f32_e32 v167, 1.0, v167
	v_add_f32_e32 v168, 1.0, v168
	v_add_f32_e32 v169, 1.0, v169
	v_add_f32_e32 v170, 1.0, v170
	v_add_f32_e32 v171, 1.0, v171
	v_add_f32_e32 v172, 1.0, v172
	v_add_f32_e32 v173, 1.0, v173
	v_rcp_f32_e32 v166, v166
	v_rcp_f32_e32 v167, v167
	v_rcp_f32_e32 v168, v168
	v_rcp_f32_e32 v169, v169
	v_rcp_f32_e32 v170, v170
	v_rcp_f32_e32 v171, v171
	v_rcp_f32_e32 v172, v172
	v_rcp_f32_e32 v173, v173
	v_mul_f32_e32 v126, v126, v166
	v_mul_f32_e32 v127, v127, v167
	v_mul_f32_e32 v128, v128, v168
	v_mul_f32_e32 v129, v129, v169
	v_mul_f32_e32 v118, v118, v170
	v_mul_f32_e32 v119, v119, v171
	v_mul_f32_e32 v120, v120, v172
	v_mul_f32_e32 v121, v121, v173
	v_mul_f32_e32 v122, v122, v126
	v_mul_f32_e32 v123, v123, v127
	v_mul_f32_e32 v124, v124, v128
	v_mul_f32_e32 v125, v125, v129
	v_mul_f32_e32 v114, v114, v118
	v_mul_f32_e32 v115, v115, v119
	v_mul_f32_e32 v116, v116, v120
	v_mul_f32_e32 v117, v117, v121
	v_cvt_pk_bf16_f32 v126, v122, v123
	v_cvt_pk_bf16_f32 v127, v124, v125
	v_cvt_pk_bf16_f32 v128, v114, v115
	v_cvt_pk_bf16_f32 v129, v116, v117
	s_nop 0
	s_waitcnt vmcnt(0)
	global_store_dwordx4 v[160:161], v[126:129], off sc1
	v_lshl_add_u64 v[160:161], s[100:101], 0, v[160:161]
	v_mul_f32_e32 v106, v106, v153
	v_mul_f32_e32 v110, v110, v153
	v_mul_f32_e32 v107, v107, v153
	v_mul_f32_e32 v111, v111, v153
	v_mul_f32_e32 v108, v108, v153
	v_mul_f32_e32 v112, v112, v153
	v_mul_f32_e32 v109, v109, v153
	v_mul_f32_e32 v113, v113, v153
	v_mul_f32_e32 v98, v98, v153
	v_mul_f32_e32 v102, v102, v153
	v_mul_f32_e32 v99, v99, v153
	v_mul_f32_e32 v103, v103, v153
	v_mul_f32_e32 v100, v100, v153
	v_mul_f32_e32 v104, v104, v153
	v_mul_f32_e32 v101, v101, v153
	v_mul_f32_e32 v105, v105, v153
	v_mul_f32_e32 v166, 0xbfb8aa3b, v110
	v_mul_f32_e32 v167, 0xbfb8aa3b, v111
	v_mul_f32_e32 v168, 0xbfb8aa3b, v112
	v_mul_f32_e32 v169, 0xbfb8aa3b, v113
	v_mul_f32_e32 v170, 0xbfb8aa3b, v102
	v_mul_f32_e32 v171, 0xbfb8aa3b, v103
	v_mul_f32_e32 v172, 0xbfb8aa3b, v104
	v_mul_f32_e32 v173, 0xbfb8aa3b, v105
	v_exp_f32_e32 v166, v166
	v_exp_f32_e32 v167, v167
	v_exp_f32_e32 v168, v168
	v_exp_f32_e32 v169, v169
	v_exp_f32_e32 v170, v170
	v_exp_f32_e32 v171, v171
	v_exp_f32_e32 v172, v172
	v_exp_f32_e32 v173, v173
	v_add_f32_e32 v166, 1.0, v166
	v_add_f32_e32 v167, 1.0, v167
	v_add_f32_e32 v168, 1.0, v168
	v_add_f32_e32 v169, 1.0, v169
	v_add_f32_e32 v170, 1.0, v170
	v_add_f32_e32 v171, 1.0, v171
	v_add_f32_e32 v172, 1.0, v172
	v_add_f32_e32 v173, 1.0, v173
	v_rcp_f32_e32 v166, v166
	v_rcp_f32_e32 v167, v167
	v_rcp_f32_e32 v168, v168
	v_rcp_f32_e32 v169, v169
	v_rcp_f32_e32 v170, v170
	v_rcp_f32_e32 v171, v171
	v_rcp_f32_e32 v172, v172
	v_rcp_f32_e32 v173, v173
	v_mul_f32_e32 v110, v110, v166
	v_mul_f32_e32 v111, v111, v167
	v_mul_f32_e32 v112, v112, v168
	v_mul_f32_e32 v113, v113, v169
	v_mul_f32_e32 v102, v102, v170
	v_mul_f32_e32 v103, v103, v171
	v_mul_f32_e32 v104, v104, v172
	v_mul_f32_e32 v105, v105, v173
	v_mul_f32_e32 v106, v106, v110
	v_mul_f32_e32 v107, v107, v111
	v_mul_f32_e32 v108, v108, v112
	v_mul_f32_e32 v109, v109, v113
	v_mul_f32_e32 v98, v98, v102
	v_mul_f32_e32 v99, v99, v103
	v_mul_f32_e32 v100, v100, v104
	v_mul_f32_e32 v101, v101, v105
	v_cvt_pk_bf16_f32 v110, v106, v107
	v_cvt_pk_bf16_f32 v111, v108, v109
	v_cvt_pk_bf16_f32 v112, v98, v99
	v_cvt_pk_bf16_f32 v113, v100, v101
	s_nop 0
	global_store_dwordx4 v[160:161], v[110:113], off sc1
	v_lshl_add_u64 v[160:161], s[100:101], 0, v[160:161]
	v_mul_f32_e32 v88, v88, v154
	v_mul_f32_e32 v92, v92, v154
	v_mul_f32_e32 v89, v89, v154
	v_mul_f32_e32 v93, v93, v154
	v_mul_f32_e32 v90, v90, v154
	v_mul_f32_e32 v94, v94, v154
	v_mul_f32_e32 v91, v91, v154
	v_mul_f32_e32 v95, v95, v154
	v_mul_f32_e32 v80, v80, v154
	v_mul_f32_e32 v84, v84, v154
	v_mul_f32_e32 v81, v81, v154
	v_mul_f32_e32 v85, v85, v154
	v_mul_f32_e32 v82, v82, v154
	v_mul_f32_e32 v86, v86, v154
	v_mul_f32_e32 v83, v83, v154
	v_mul_f32_e32 v87, v87, v154
	v_mul_f32_e32 v166, 0xbfb8aa3b, v92
	v_mul_f32_e32 v167, 0xbfb8aa3b, v93
	v_mul_f32_e32 v168, 0xbfb8aa3b, v94
	v_mul_f32_e32 v169, 0xbfb8aa3b, v95
	v_mul_f32_e32 v170, 0xbfb8aa3b, v84
	v_mul_f32_e32 v171, 0xbfb8aa3b, v85
	v_mul_f32_e32 v172, 0xbfb8aa3b, v86
	v_mul_f32_e32 v173, 0xbfb8aa3b, v87
	v_exp_f32_e32 v166, v166
	v_exp_f32_e32 v167, v167
	v_exp_f32_e32 v168, v168
	v_exp_f32_e32 v169, v169
	v_exp_f32_e32 v170, v170
	v_exp_f32_e32 v171, v171
	v_exp_f32_e32 v172, v172
	v_exp_f32_e32 v173, v173
	v_add_f32_e32 v166, 1.0, v166
	v_add_f32_e32 v167, 1.0, v167
	v_add_f32_e32 v168, 1.0, v168
	v_add_f32_e32 v169, 1.0, v169
	v_add_f32_e32 v170, 1.0, v170
	v_add_f32_e32 v171, 1.0, v171
	v_add_f32_e32 v172, 1.0, v172
	v_add_f32_e32 v173, 1.0, v173
	v_rcp_f32_e32 v166, v166
	v_rcp_f32_e32 v167, v167
	v_rcp_f32_e32 v168, v168
	v_rcp_f32_e32 v169, v169
	v_rcp_f32_e32 v170, v170
	v_rcp_f32_e32 v171, v171
	v_rcp_f32_e32 v172, v172
	v_rcp_f32_e32 v173, v173
	v_mul_f32_e32 v92, v92, v166
	v_mul_f32_e32 v93, v93, v167
	v_mul_f32_e32 v94, v94, v168
	v_mul_f32_e32 v95, v95, v169
	v_mul_f32_e32 v84, v84, v170
	v_mul_f32_e32 v85, v85, v171
	v_mul_f32_e32 v86, v86, v172
	v_mul_f32_e32 v87, v87, v173
	v_mul_f32_e32 v88, v88, v92
	v_mul_f32_e32 v89, v89, v93
	v_mul_f32_e32 v90, v90, v94
	v_mul_f32_e32 v91, v91, v95
	v_mul_f32_e32 v80, v80, v84
	v_mul_f32_e32 v81, v81, v85
	v_mul_f32_e32 v82, v82, v86
	v_mul_f32_e32 v83, v83, v87
	v_cvt_pk_bf16_f32 v92, v88, v89
	v_cvt_pk_bf16_f32 v93, v90, v91
	v_cvt_pk_bf16_f32 v94, v80, v81
	v_cvt_pk_bf16_f32 v95, v82, v83
	s_nop 0
	global_store_dwordx4 v[160:161], v[92:95], off sc1
	v_lshl_add_u64 v[160:161], s[100:101], 0, v[160:161]
	v_mul_f32_e32 v72, v72, v155
	v_mul_f32_e32 v76, v76, v155
	v_mul_f32_e32 v73, v73, v155
	v_mul_f32_e32 v77, v77, v155
	v_mul_f32_e32 v74, v74, v155
	v_mul_f32_e32 v78, v78, v155
	v_mul_f32_e32 v75, v75, v155
	v_mul_f32_e32 v79, v79, v155
	v_mul_f32_e32 v64, v64, v155
	v_mul_f32_e32 v68, v68, v155
	v_mul_f32_e32 v65, v65, v155
	v_mul_f32_e32 v69, v69, v155
	v_mul_f32_e32 v66, v66, v155
	v_mul_f32_e32 v70, v70, v155
	v_mul_f32_e32 v67, v67, v155
	v_mul_f32_e32 v71, v71, v155
	v_mul_f32_e32 v166, 0xbfb8aa3b, v76
	v_mul_f32_e32 v167, 0xbfb8aa3b, v77
	v_mul_f32_e32 v168, 0xbfb8aa3b, v78
	v_mul_f32_e32 v169, 0xbfb8aa3b, v79
	v_mul_f32_e32 v170, 0xbfb8aa3b, v68
	v_mul_f32_e32 v171, 0xbfb8aa3b, v69
	v_mul_f32_e32 v172, 0xbfb8aa3b, v70
	v_mul_f32_e32 v173, 0xbfb8aa3b, v71
	v_exp_f32_e32 v166, v166
	v_exp_f32_e32 v167, v167
	v_exp_f32_e32 v168, v168
	v_exp_f32_e32 v169, v169
	v_exp_f32_e32 v170, v170
	v_exp_f32_e32 v171, v171
	v_exp_f32_e32 v172, v172
	v_exp_f32_e32 v173, v173
	v_add_f32_e32 v166, 1.0, v166
	v_add_f32_e32 v167, 1.0, v167
	v_add_f32_e32 v168, 1.0, v168
	v_add_f32_e32 v169, 1.0, v169
	v_add_f32_e32 v170, 1.0, v170
	v_add_f32_e32 v171, 1.0, v171
	v_add_f32_e32 v172, 1.0, v172
	v_add_f32_e32 v173, 1.0, v173
	v_rcp_f32_e32 v166, v166
	v_rcp_f32_e32 v167, v167
	v_rcp_f32_e32 v168, v168
	v_rcp_f32_e32 v169, v169
	v_rcp_f32_e32 v170, v170
	v_rcp_f32_e32 v171, v171
	v_rcp_f32_e32 v172, v172
	v_rcp_f32_e32 v173, v173
	v_mul_f32_e32 v76, v76, v166
	v_mul_f32_e32 v77, v77, v167
	v_mul_f32_e32 v78, v78, v168
	v_mul_f32_e32 v79, v79, v169
	v_mul_f32_e32 v68, v68, v170
	v_mul_f32_e32 v69, v69, v171
	v_mul_f32_e32 v70, v70, v172
	v_mul_f32_e32 v71, v71, v173
	v_mul_f32_e32 v72, v72, v76
	v_mul_f32_e32 v73, v73, v77
	v_mul_f32_e32 v74, v74, v78
	v_mul_f32_e32 v75, v75, v79
	v_mul_f32_e32 v64, v64, v68
	v_mul_f32_e32 v65, v65, v69
	v_mul_f32_e32 v66, v66, v70
	v_mul_f32_e32 v67, v67, v71
	v_cvt_pk_bf16_f32 v76, v72, v73
	v_cvt_pk_bf16_f32 v77, v74, v75
	v_cvt_pk_bf16_f32 v78, v64, v65
	v_cvt_pk_bf16_f32 v79, v66, v67
	s_nop 0
	global_store_dwordx4 v[160:161], v[76:79], off sc1
	v_lshl_add_u64 v[160:161], s[98:99], 0, v[160:161]
	v_mul_f32_e32 v56, v56, v156
	v_mul_f32_e32 v60, v60, v156
	v_mul_f32_e32 v57, v57, v156
	v_mul_f32_e32 v61, v61, v156
	v_mul_f32_e32 v58, v58, v156
	v_mul_f32_e32 v62, v62, v156
	v_mul_f32_e32 v59, v59, v156
	v_mul_f32_e32 v63, v63, v156
	v_mul_f32_e32 v48, v48, v156
	v_mul_f32_e32 v52, v52, v156
	v_mul_f32_e32 v49, v49, v156
	v_mul_f32_e32 v53, v53, v156
	v_mul_f32_e32 v50, v50, v156
	v_mul_f32_e32 v54, v54, v156
	v_mul_f32_e32 v51, v51, v156
	v_mul_f32_e32 v55, v55, v156
	v_mul_f32_e32 v166, 0xbfb8aa3b, v60
	v_mul_f32_e32 v167, 0xbfb8aa3b, v61
	v_mul_f32_e32 v168, 0xbfb8aa3b, v62
	v_mul_f32_e32 v169, 0xbfb8aa3b, v63
	v_mul_f32_e32 v170, 0xbfb8aa3b, v52
	v_mul_f32_e32 v171, 0xbfb8aa3b, v53
	v_mul_f32_e32 v172, 0xbfb8aa3b, v54
	v_mul_f32_e32 v173, 0xbfb8aa3b, v55
	v_exp_f32_e32 v166, v166
	v_exp_f32_e32 v167, v167
	v_exp_f32_e32 v168, v168
	v_exp_f32_e32 v169, v169
	v_exp_f32_e32 v170, v170
	v_exp_f32_e32 v171, v171
	v_exp_f32_e32 v172, v172
	v_exp_f32_e32 v173, v173
	v_add_f32_e32 v166, 1.0, v166
	v_add_f32_e32 v167, 1.0, v167
	v_add_f32_e32 v168, 1.0, v168
	v_add_f32_e32 v169, 1.0, v169
	v_add_f32_e32 v170, 1.0, v170
	v_add_f32_e32 v171, 1.0, v171
	v_add_f32_e32 v172, 1.0, v172
	v_add_f32_e32 v173, 1.0, v173
	v_rcp_f32_e32 v166, v166
	v_rcp_f32_e32 v167, v167
	v_rcp_f32_e32 v168, v168
	v_rcp_f32_e32 v169, v169
	v_rcp_f32_e32 v170, v170
	v_rcp_f32_e32 v171, v171
	v_rcp_f32_e32 v172, v172
	v_rcp_f32_e32 v173, v173
	v_mul_f32_e32 v60, v60, v166
	v_mul_f32_e32 v61, v61, v167
	v_mul_f32_e32 v62, v62, v168
	v_mul_f32_e32 v63, v63, v169
	v_mul_f32_e32 v52, v52, v170
	v_mul_f32_e32 v53, v53, v171
	v_mul_f32_e32 v54, v54, v172
	v_mul_f32_e32 v55, v55, v173
	v_mul_f32_e32 v56, v56, v60
	v_mul_f32_e32 v57, v57, v61
	v_mul_f32_e32 v58, v58, v62
	v_mul_f32_e32 v59, v59, v63
	v_mul_f32_e32 v48, v48, v52
	v_mul_f32_e32 v49, v49, v53
	v_mul_f32_e32 v50, v50, v54
	v_mul_f32_e32 v51, v51, v55
	v_cvt_pk_bf16_f32 v60, v56, v57
	v_cvt_pk_bf16_f32 v61, v58, v59
	v_cvt_pk_bf16_f32 v62, v48, v49
	v_cvt_pk_bf16_f32 v63, v50, v51
	s_nop 0
	global_store_dwordx4 v[160:161], v[60:63], off sc1
	v_lshl_add_u64 v[160:161], s[100:101], 0, v[160:161]
	v_mul_f32_e32 v40, v40, v157
	v_mul_f32_e32 v44, v44, v157
	v_mul_f32_e32 v41, v41, v157
	v_mul_f32_e32 v45, v45, v157
	v_mul_f32_e32 v42, v42, v157
	v_mul_f32_e32 v46, v46, v157
	v_mul_f32_e32 v43, v43, v157
	v_mul_f32_e32 v47, v47, v157
	v_mul_f32_e32 v32, v32, v157
	v_mul_f32_e32 v36, v36, v157
	v_mul_f32_e32 v33, v33, v157
	v_mul_f32_e32 v37, v37, v157
	v_mul_f32_e32 v34, v34, v157
	v_mul_f32_e32 v38, v38, v157
	v_mul_f32_e32 v35, v35, v157
	v_mul_f32_e32 v39, v39, v157
	v_mul_f32_e32 v166, 0xbfb8aa3b, v44
	v_mul_f32_e32 v167, 0xbfb8aa3b, v45
	v_mul_f32_e32 v168, 0xbfb8aa3b, v46
	v_mul_f32_e32 v169, 0xbfb8aa3b, v47
	v_mul_f32_e32 v170, 0xbfb8aa3b, v36
	v_mul_f32_e32 v171, 0xbfb8aa3b, v37
	v_mul_f32_e32 v172, 0xbfb8aa3b, v38
	v_mul_f32_e32 v173, 0xbfb8aa3b, v39
	v_exp_f32_e32 v166, v166
	v_exp_f32_e32 v167, v167
	v_exp_f32_e32 v168, v168
	v_exp_f32_e32 v169, v169
	v_exp_f32_e32 v170, v170
	v_exp_f32_e32 v171, v171
	v_exp_f32_e32 v172, v172
	v_exp_f32_e32 v173, v173
	v_add_f32_e32 v166, 1.0, v166
	v_add_f32_e32 v167, 1.0, v167
	v_add_f32_e32 v168, 1.0, v168
	v_add_f32_e32 v169, 1.0, v169
	v_add_f32_e32 v170, 1.0, v170
	v_add_f32_e32 v171, 1.0, v171
	v_add_f32_e32 v172, 1.0, v172
	v_add_f32_e32 v173, 1.0, v173
	v_rcp_f32_e32 v166, v166
	v_rcp_f32_e32 v167, v167
	v_rcp_f32_e32 v168, v168
	v_rcp_f32_e32 v169, v169
	v_rcp_f32_e32 v170, v170
	v_rcp_f32_e32 v171, v171
	v_rcp_f32_e32 v172, v172
	v_rcp_f32_e32 v173, v173
	v_mul_f32_e32 v44, v44, v166
	v_mul_f32_e32 v45, v45, v167
	v_mul_f32_e32 v46, v46, v168
	v_mul_f32_e32 v47, v47, v169
	v_mul_f32_e32 v36, v36, v170
	v_mul_f32_e32 v37, v37, v171
	v_mul_f32_e32 v38, v38, v172
	v_mul_f32_e32 v39, v39, v173
	v_mul_f32_e32 v40, v40, v44
	v_mul_f32_e32 v41, v41, v45
	v_mul_f32_e32 v42, v42, v46
	v_mul_f32_e32 v43, v43, v47
	v_mul_f32_e32 v32, v32, v36
	v_mul_f32_e32 v33, v33, v37
	v_mul_f32_e32 v34, v34, v38
	v_mul_f32_e32 v35, v35, v39
	v_cvt_pk_bf16_f32 v44, v40, v41
	v_cvt_pk_bf16_f32 v45, v42, v43
	v_cvt_pk_bf16_f32 v46, v32, v33
	v_cvt_pk_bf16_f32 v47, v34, v35
	s_nop 0
	global_store_dwordx4 v[160:161], v[44:47], off sc1
	v_lshl_add_u64 v[160:161], s[100:101], 0, v[160:161]
	v_mul_f32_e32 v24, v24, v158
	v_mul_f32_e32 v28, v28, v158
	v_mul_f32_e32 v25, v25, v158
	v_mul_f32_e32 v29, v29, v158
	v_mul_f32_e32 v26, v26, v158
	v_mul_f32_e32 v30, v30, v158
	v_mul_f32_e32 v27, v27, v158
	v_mul_f32_e32 v31, v31, v158
	v_mul_f32_e32 v16, v16, v158
	v_mul_f32_e32 v20, v20, v158
	v_mul_f32_e32 v17, v17, v158
	v_mul_f32_e32 v21, v21, v158
	v_mul_f32_e32 v18, v18, v158
	v_mul_f32_e32 v22, v22, v158
	v_mul_f32_e32 v19, v19, v158
	v_mul_f32_e32 v23, v23, v158
	v_mul_f32_e32 v166, 0xbfb8aa3b, v28
	v_mul_f32_e32 v167, 0xbfb8aa3b, v29
	v_mul_f32_e32 v168, 0xbfb8aa3b, v30
	v_mul_f32_e32 v169, 0xbfb8aa3b, v31
	v_mul_f32_e32 v170, 0xbfb8aa3b, v20
	v_mul_f32_e32 v171, 0xbfb8aa3b, v21
	v_mul_f32_e32 v172, 0xbfb8aa3b, v22
	v_mul_f32_e32 v173, 0xbfb8aa3b, v23
	v_exp_f32_e32 v166, v166
	v_exp_f32_e32 v167, v167
	v_exp_f32_e32 v168, v168
	v_exp_f32_e32 v169, v169
	v_exp_f32_e32 v170, v170
	v_exp_f32_e32 v171, v171
	v_exp_f32_e32 v172, v172
	v_exp_f32_e32 v173, v173
	v_add_f32_e32 v166, 1.0, v166
	v_add_f32_e32 v167, 1.0, v167
	v_add_f32_e32 v168, 1.0, v168
	v_add_f32_e32 v169, 1.0, v169
	v_add_f32_e32 v170, 1.0, v170
	v_add_f32_e32 v171, 1.0, v171
	v_add_f32_e32 v172, 1.0, v172
	v_add_f32_e32 v173, 1.0, v173
	v_rcp_f32_e32 v166, v166
	v_rcp_f32_e32 v167, v167
	v_rcp_f32_e32 v168, v168
	v_rcp_f32_e32 v169, v169
	v_rcp_f32_e32 v170, v170
	v_rcp_f32_e32 v171, v171
	v_rcp_f32_e32 v172, v172
	v_rcp_f32_e32 v173, v173
	v_mul_f32_e32 v28, v28, v166
	v_mul_f32_e32 v29, v29, v167
	v_mul_f32_e32 v30, v30, v168
	v_mul_f32_e32 v31, v31, v169
	v_mul_f32_e32 v20, v20, v170
	v_mul_f32_e32 v21, v21, v171
	v_mul_f32_e32 v22, v22, v172
	v_mul_f32_e32 v23, v23, v173
	v_mul_f32_e32 v24, v24, v28
	v_mul_f32_e32 v25, v25, v29
	v_mul_f32_e32 v26, v26, v30
	v_mul_f32_e32 v27, v27, v31
	v_mul_f32_e32 v16, v16, v20
	v_mul_f32_e32 v17, v17, v21
	v_mul_f32_e32 v18, v18, v22
	v_mul_f32_e32 v19, v19, v23
	v_cvt_pk_bf16_f32 v28, v24, v25
	v_cvt_pk_bf16_f32 v29, v26, v27
	v_cvt_pk_bf16_f32 v30, v16, v17
	v_cvt_pk_bf16_f32 v31, v18, v19
	s_nop 0
	global_store_dwordx4 v[160:161], v[28:31], off sc1
	v_lshl_add_u64 v[160:161], s[100:101], 0, v[160:161]
	v_mul_f32_e32 v8, v8, v159
	v_mul_f32_e32 v12, v12, v159
	v_mul_f32_e32 v9, v9, v159
	v_mul_f32_e32 v13, v13, v159
	v_mul_f32_e32 v10, v10, v159
	v_mul_f32_e32 v14, v14, v159
	v_mul_f32_e32 v11, v11, v159
	v_mul_f32_e32 v15, v15, v159
	v_mul_f32_e32 v0, v0, v159
	v_mul_f32_e32 v4, v4, v159
	v_mul_f32_e32 v1, v1, v159
	v_mul_f32_e32 v5, v5, v159
	v_mul_f32_e32 v2, v2, v159
	v_mul_f32_e32 v6, v6, v159
	v_mul_f32_e32 v3, v3, v159
	v_mul_f32_e32 v7, v7, v159
	v_mul_f32_e32 v166, 0xbfb8aa3b, v12
	v_mul_f32_e32 v167, 0xbfb8aa3b, v13
	v_mul_f32_e32 v168, 0xbfb8aa3b, v14
	v_mul_f32_e32 v169, 0xbfb8aa3b, v15
	v_mul_f32_e32 v170, 0xbfb8aa3b, v4
	v_mul_f32_e32 v171, 0xbfb8aa3b, v5
	v_mul_f32_e32 v172, 0xbfb8aa3b, v6
	v_mul_f32_e32 v173, 0xbfb8aa3b, v7
	v_exp_f32_e32 v166, v166
	v_exp_f32_e32 v167, v167
	v_exp_f32_e32 v168, v168
	v_exp_f32_e32 v169, v169
	v_exp_f32_e32 v170, v170
	v_exp_f32_e32 v171, v171
	v_exp_f32_e32 v172, v172
	v_exp_f32_e32 v173, v173
	v_add_f32_e32 v166, 1.0, v166
	v_add_f32_e32 v167, 1.0, v167
	v_add_f32_e32 v168, 1.0, v168
	v_add_f32_e32 v169, 1.0, v169
	v_add_f32_e32 v170, 1.0, v170
	v_add_f32_e32 v171, 1.0, v171
	v_add_f32_e32 v172, 1.0, v172
	v_add_f32_e32 v173, 1.0, v173
	v_rcp_f32_e32 v166, v166
	v_rcp_f32_e32 v167, v167
	v_rcp_f32_e32 v168, v168
	v_rcp_f32_e32 v169, v169
	v_rcp_f32_e32 v170, v170
	v_rcp_f32_e32 v171, v171
	v_rcp_f32_e32 v172, v172
	v_rcp_f32_e32 v173, v173
	v_mul_f32_e32 v12, v12, v166
	v_mul_f32_e32 v13, v13, v167
	v_mul_f32_e32 v14, v14, v168
	v_mul_f32_e32 v15, v15, v169
	v_mul_f32_e32 v4, v4, v170
	v_mul_f32_e32 v5, v5, v171
	v_mul_f32_e32 v6, v6, v172
	v_mul_f32_e32 v7, v7, v173
	v_mul_f32_e32 v8, v8, v12
	v_mul_f32_e32 v9, v9, v13
	v_mul_f32_e32 v10, v10, v14
	v_mul_f32_e32 v11, v11, v15
	v_mul_f32_e32 v0, v0, v4
	v_mul_f32_e32 v1, v1, v5
	v_mul_f32_e32 v2, v2, v6
	v_mul_f32_e32 v3, v3, v7
	v_cvt_pk_bf16_f32 v12, v8, v9
	v_cvt_pk_bf16_f32 v13, v10, v11
	v_cvt_pk_bf16_f32 v14, v0, v1
	v_cvt_pk_bf16_f32 v15, v2, v3
	s_nop 0
	global_store_dwordx4 v[160:161], v[12:15], off sc1
	s_nop 1
	s_mov_b64 s[22:23], -1
	s_cbranch_vccnz .LBB0_142
	s_andn2_b64 vcc, exec, s[6:7]
	s_cbranch_vccnz .LBB0_141
	s_barrier
	s_branch .LBB0_141
